# attention A: staging LDS writes issued two S-MFMA gaps earlier (right after the second S MFMA, ahead of the K-fragment reads)
# speedup vs baseline: 1.0059x; 1.0059x over previous
; #define FLAS __attribute__((address_space(3)))
; #define FA_SB() __builtin_amdgcn_sched_barrier(0)
; #define FA_EXP2(J, PX, R) do { const float e0_ = __builtin_amdgcn_exp2f(PX[R]), e1_ = __builtin_amdgcn_exp2f(PX[(R) + 1]); ps += e0_; ps += e1_; PWN[(J) >> 2][(J) & 3] = cvtpk(e0_, e1_); } while (0)
; __device__ __forceinline__ void attn_unit_a(FLAS unsigned char* lds, const Unit u) {
;     ...
;         if (ziN) { pN0 = __builtin_amdgcn_mfma_f32_32x32x16_bf16(kf[0], qr[0], z16, 0, 0, 0); FA_EXP2(8, pC1, 0); FA_SB(); pN1 = __builtin_amdgcn_mfma_f32_32x32x16_bf16(kf[1], qr[0], z16, 0, 0, 0); }
;         else { pN0 = __builtin_amdgcn_mfma_f32_32x32x16_bf16(kf[0], qr[0], pN0, 0, 0, 0); FA_EXP2(8, pC1, 0); FA_SB(); pN1 = __builtin_amdgcn_mfma_f32_32x32x16_bf16(kf[1], qr[0], pN1, 0, 0, 0); }
;         kf[0] = FA_KF(2, 0); kf[1] = FA_KF(2, 1); FA_EXP2(9, pC1, 2); FA_SB();
;         pN0 = __builtin_amdgcn_mfma_f32_32x32x16_bf16(kf[2], qr[1], pN0, 0, 0, 0); FA_EXP2(10, pC1, 4); FA_SB();
;         pN1 = __builtin_amdgcn_mfma_f32_32x32x16_bf16(kf[3], qr[1], pN1, 0, 0, 0); kf[2] = FA_KF(3, 0); kf[3] = FA_KF(3, 1); FA_EXP2(11, pC1, 6); FA_SB();
;         pN0 = __builtin_amdgcn_mfma_f32_32x32x16_bf16(kf[0], qr[2], pN0, 0, 0, 0); FA_EXP2(12, pC1, 8); FA_SB();
;         pN1 = __builtin_amdgcn_mfma_f32_32x32x16_bf16(kf[1], qr[2], pN1, 0, 0, 0); FA_EXP2(13, pC1, 10); FA_SB();
;         pN0 = __builtin_amdgcn_mfma_f32_32x32x16_bf16(kf[2], qr[3], pN0, 0, 0, 0); FA_EXP2(14, pC1, 12); FA_SB();
;         pN1 = __builtin_amdgcn_mfma_f32_32x32x16_bf16(kf[3], qr[3], pN1, 0, 0, 0); FA_EXP2(15, pC1, 14); FA_SB();
;     ...
;         lsum += ps; cbC = cbN;
;         if (i + 2 < NT) { *(FLAS u32x4*)(lds + LA_K + (i & 1) * KBUF + kdst) = kreg;
; #pragma unroll
;             for (int j = 0; j < 2; ++j) { *(FLAS u32x2*)(lds + LA_V + ((i + 2) & 3) * VBUF + vdst + j * 64 * VPITCH) = (u32x2){vreg[j].x, vreg[j].y}; *(FLAS u32x2*)(lds + LA_V + ((i + 2) & 3) * VBUF + vdst + j * 64 * VPITCH + 16) = (u32x2){vreg[j].z, vreg[j].w}; } }
.Lk2_e:
	s_add_i32 s34, s19, 2
	s_and_b32 s0, s34, 2
	s_mulk_i32 s0, 0x4800
	v_add_u32_e32 v188, s0, v245
	v_add_u32_e32 v189, 0x4000, v188
	v_add_u32_e32 v188, 0x6000, v188
	s_waitcnt vmcnt(2)
	ds_write_b128 v225, v[176:179]
	s_waitcnt vmcnt(1)
	ds_write2_b64 v189, v[180:181], v[182:183] offset1:2
	s_waitcnt vmcnt(0)
	ds_write2_b64 v188, v[184:185], v[186:187] offset0:128 offset1:130
	ds_read_b128 v[128:131], v249 offset:8192
	ds_read_b128 v[132:135], v249 offset:8704
	v_mfma_f32_32x32x16_bf16 v[64:79], v[196:199], v[164:167], v[64:79]
	v_exp_f32_e32 v116, v116
	v_exp_f32_e32 v117, v117
	v_mfma_f32_32x32x16_bf16 v[80:95], v[192:195], v[164:167], v[80:95]
	ds_read_b128 v[136:139], v250 offset:8192
	ds_read_b128 v[140:143], v250 offset:8704
	v_exp_f32_e32 v118, v118
	v_exp_f32_e32 v119, v119
	s_and_b32 s0, s19, 2
	s_mulk_i32 s0, 0x4800
	v_add_u32_e32 v201, s0, v251
	s_waitcnt lgkmcnt(2)
	v_mfma_f32_32x32x16_bf16 v[64:79], v[128:131], v[168:171], v[64:79]
	ds_read_b128 v[128:131], v201 offset:16384
	v_exp_f32_e32 v120, v120
	v_exp_f32_e32 v121, v121
	v_mfma_f32_32x32x16_bf16 v[80:95], v[132:135], v[168:171], v[80:95]
	ds_read_b128 v[132:135], v201 offset:20992
	v_exp_f32_e32 v122, v122
	v_exp_f32_e32 v123, v123
	s_waitcnt lgkmcnt(2)
	v_mfma_f32_32x32x16_bf16 v[64:79], v[136:139], v[172:175], v[64:79]
	ds_read_b128 v[136:139], v201 offset:25600
	v_exp_f32_e32 v124, v124
	v_exp_f32_e32 v125, v125
	v_mfma_f32_32x32x16_bf16 v[80:95], v[140:143], v[172:175], v[80:95]
	v_exp_f32_e32 v126, v126
	v_exp_f32_e32 v127, v127
	v_cvt_pk_bf16_f32 v140, v96, v97
	v_cvt_pk_bf16_f32 v141, v98, v99
	v_cvt_pk_bf16_f32 v142, v100, v101
	v_cvt_pk_bf16_f32 v143, v102, v103

; #define FLAS __attribute__((address_space(3)))
; #define FA_SB() __builtin_amdgcn_sched_barrier(0)
; #define FA_EXP2(J, PX, R) do { const float e0_ = __builtin_amdgcn_exp2f(PX[R]), e1_ = __builtin_amdgcn_exp2f(PX[(R) + 1]); ps += e0_; ps += e1_; PWN[(J) >> 2][(J) & 3] = cvtpk(e0_, e1_); } while (0)
; __device__ __forceinline__ void attn_unit_a(FLAS unsigned char* lds, const Unit u) {
;     ...
;         if (ziN) { pN0 = __builtin_amdgcn_mfma_f32_32x32x16_bf16(kf[0], qr[0], z16, 0, 0, 0); FA_EXP2(8, pC1, 0); FA_SB(); pN1 = __builtin_amdgcn_mfma_f32_32x32x16_bf16(kf[1], qr[0], z16, 0, 0, 0); }
;         else { pN0 = __builtin_amdgcn_mfma_f32_32x32x16_bf16(kf[0], qr[0], pN0, 0, 0, 0); FA_EXP2(8, pC1, 0); FA_SB(); pN1 = __builtin_amdgcn_mfma_f32_32x32x16_bf16(kf[1], qr[0], pN1, 0, 0, 0); }
;         kf[0] = FA_KF(2, 0); kf[1] = FA_KF(2, 1); FA_EXP2(9, pC1, 2); FA_SB();
;         pN0 = __builtin_amdgcn_mfma_f32_32x32x16_bf16(kf[2], qr[1], pN0, 0, 0, 0); FA_EXP2(10, pC1, 4); FA_SB();
;         pN1 = __builtin_amdgcn_mfma_f32_32x32x16_bf16(kf[3], qr[1], pN1, 0, 0, 0); kf[2] = FA_KF(3, 0); kf[3] = FA_KF(3, 1); FA_EXP2(11, pC1, 6); FA_SB();
;         pN0 = __builtin_amdgcn_mfma_f32_32x32x16_bf16(kf[0], qr[2], pN0, 0, 0, 0); FA_EXP2(12, pC1, 8); FA_SB();
;         pN1 = __builtin_amdgcn_mfma_f32_32x32x16_bf16(kf[1], qr[2], pN1, 0, 0, 0); FA_EXP2(13, pC1, 10); FA_SB();
;         pN0 = __builtin_amdgcn_mfma_f32_32x32x16_bf16(kf[2], qr[3], pN0, 0, 0, 0); FA_EXP2(14, pC1, 12); FA_SB();
;         pN1 = __builtin_amdgcn_mfma_f32_32x32x16_bf16(kf[3], qr[3], pN1, 0, 0, 0); FA_EXP2(15, pC1, 14); FA_SB();
;     ...
;         lsum += ps; cbC = cbN;
;         if (i + 2 < NT) { *(FLAS u32x4*)(lds + LA_K + (i & 1) * KBUF + kdst) = kreg;
; #pragma unroll
;             for (int j = 0; j < 2; ++j) { *(FLAS u32x2*)(lds + LA_V + ((i + 2) & 3) * VBUF + vdst + j * 64 * VPITCH) = (u32x2){vreg[j].x, vreg[j].y}; *(FLAS u32x2*)(lds + LA_V + ((i + 2) & 3) * VBUF + vdst + j * 64 * VPITCH + 16) = (u32x2){vreg[j].z, vreg[j].w}; } }
.Lk2_o:
	v_add_u32_e32 v204, s18, v245
	v_add_u32_e32 v205, 0x4000, v204
	v_add_u32_e32 v204, 0x6000, v204
	s_waitcnt vmcnt(2)
	ds_write_b128 v225, v[176:179] offset:8192
	s_waitcnt vmcnt(1)
	ds_write2_b64 v205, v[180:181], v[182:183] offset1:2
	s_waitcnt vmcnt(0)
	ds_write2_b64 v204, v[184:185], v[186:187] offset0:128 offset1:130
	ds_read_b128 v[128:131], v249
	ds_read_b128 v[132:135], v249 offset:512
	v_mfma_f32_32x32x16_bf16 v[96:111], v[192:195], v[164:167], v[96:111]
	v_exp_f32_e32 v84, v84
	v_exp_f32_e32 v85, v85
	v_mfma_f32_32x32x16_bf16 v[112:127], v[188:191], v[164:167], v[112:127]
	ds_read_b128 v[136:139], v250
	ds_read_b128 v[140:143], v250 offset:512
	v_exp_f32_e32 v86, v86
	v_exp_f32_e32 v87, v87
	s_add_i32 s12, s34, -1
	s_and_b32 s18, s12, 3
	s_mulk_i32 s18, 0x4800
	v_add_u32_e32 v200, s18, v251
	s_waitcnt lgkmcnt(2)
	v_mfma_f32_32x32x16_bf16 v[96:111], v[128:131], v[168:171], v[96:111]
	ds_read_b128 v[128:131], v200 offset:16384
	v_exp_f32_e32 v88, v88
	v_exp_f32_e32 v89, v89
	v_mfma_f32_32x32x16_bf16 v[112:127], v[132:135], v[168:171], v[112:127]
	ds_read_b128 v[132:135], v200 offset:20992
	v_exp_f32_e32 v90, v90
	v_exp_f32_e32 v91, v91
	s_waitcnt lgkmcnt(2)
	v_mfma_f32_32x32x16_bf16 v[96:111], v[136:139], v[172:175], v[96:111]
	ds_read_b128 v[136:139], v200 offset:25600
	v_exp_f32_e32 v92, v92
	v_exp_f32_e32 v93, v93
	v_mfma_f32_32x32x16_bf16 v[112:127], v[140:143], v[172:175], v[112:127]
	v_exp_f32_e32 v94, v94
	v_exp_f32_e32 v95, v95
